# in-loop grid barriers: all waiters poll the TOP arrival counter (TOP >= nx*(gen+1)) instead of waiting for the TOPGEN bump
# speedup vs baseline: 1.0036x; 1.0036x over previous
.LBB0_380:
	s_or_b64 exec, exec, s[10:11]
	v_cvt_f32_u32_e32 v6, v4
	s_waitcnt vmcnt(0)
	v_readfirstlane_b32 s10, v5
	v_sub_u32_e32 v5, 0, v4
	v_rcp_iflag_f32_e32 v6, v6
	v_add_u32_e32 v7, s10, v3
	v_mul_f32_e32 v6, 0x4f7ffffe, v6
	v_cvt_u32_f32_e32 v6, v6
	v_mul_lo_u32 v3, v5, v6
	v_mul_hi_u32 v3, v6, v3
	v_add_u32_e32 v3, v6, v3
	v_mul_hi_u32 v3, v7, v3
	v_mul_lo_u32 v5, v3, v4
	v_sub_u32_e32 v5, v7, v5
	v_add_u32_e32 v6, 1, v3
	v_cmp_ge_u32_e32 vcc, v5, v4
	s_nop 1
	v_cndmask_b32_e32 v3, v3, v6, vcc
	v_sub_u32_e32 v6, v5, v4
	v_cndmask_b32_e32 v5, v5, v6, vcc
	v_add_u32_e32 v6, 1, v3
	v_cmp_ge_u32_e32 vcc, v5, v4
	v_add_u32_e32 v5, 1, v7
	s_nop 0
	v_cndmask_b32_e32 v3, v3, v6, vcc
	v_mul_lo_u32 v6, v4, v3
	v_add_u32_e32 v4, v6, v4
	v_cmp_ne_u32_e32 vcc, v5, v4
	s_and_saveexec_b64 s[10:11], vcc
	s_xor_b64 s[10:11], exec, s[10:11]
	s_cbranch_execz .LBB0_394
	v_readlane_b32 s14, v245, 63
	v_readlane_b32 s15, v244, 0
	s_waitcnt lgkmcnt(0)
	v_add_u32_e32 v204, 1, v3
	v_mul_lo_u32 v204, v204, v2
	s_nop 3
	global_load_dword v2, v173, s[14:15] sc1
	s_waitcnt vmcnt(0)
	v_cmp_lt_u32_e32 vcc, v2, v204
	s_and_saveexec_b64 s[14:15], vcc
	s_cbranch_execz .LBB0_393
	s_mov_b32 s39, 1
	s_mov_b64 s[18:19], 0
	s_branch .LBB0_384

.LBB0_386:
	v_readlane_b32 s22, v245, 63
	v_readlane_b32 s23, v244, 0
	s_add_i32 s39, s39, 1
	s_mov_b64 s[28:29], -1
	s_nop 2
	global_load_dword v2, v173, s[22:23] sc1
	s_waitcnt vmcnt(0)
	v_cmp_ge_u32_e32 vcc, v2, v204
	s_orn2_b64 s[22:23], vcc, exec
	s_branch .LBB0_383

.LBB0_397:
	s_or_b64 exec, exec, s[14:15]
	s_waitcnt vmcnt(0)
	v_readfirstlane_b32 s10, v4
	v_cvt_f32_u32_e32 v4, v2
	v_sub_u32_e32 v5, 0, v2
	v_add_u32_e32 v3, s10, v3
	v_readlane_b32 s10, v244, 1
	v_rcp_iflag_f32_e32 v4, v4
	v_readlane_b32 s11, v244, 2
	s_mov_b64 s[14:15], -1
	v_mul_f32_e32 v4, 0x4f7ffffe, v4
	v_cvt_u32_f32_e32 v4, v4
	v_mul_lo_u32 v5, v5, v4
	v_mul_hi_u32 v5, v4, v5
	v_add_u32_e32 v4, v4, v5
	v_mul_hi_u32 v4, v3, v4
	v_mul_lo_u32 v5, v4, v2
	v_sub_u32_e32 v5, v3, v5
	v_cmp_ge_u32_e32 vcc, v5, v2
	v_add_u32_e32 v6, 1, v4
	v_add_u32_e32 v3, 1, v3
	v_cndmask_b32_e32 v4, v4, v6, vcc
	v_sub_u32_e32 v6, v5, v2
	v_cndmask_b32_e32 v5, v5, v6, vcc
	v_cmp_ge_u32_e32 vcc, v5, v2
	v_add_u32_e32 v5, 1, v4
	s_nop 0
	v_cndmask_b32_e32 v4, v4, v5, vcc
	v_mul_lo_u32 v5, v2, v4
	v_add_u32_e32 v2, v5, v2
	v_mov_b32_e32 v204, v2
	v_cmp_ne_u32_e32 vcc, v3, v2
	v_mov_b64_e32 v[2:3], s[10:11]
	s_and_saveexec_b64 s[10:11], vcc
	s_cbranch_execz .LBB0_409
	v_readlane_b32 s14, v245, 63
	v_readlane_b32 s15, v244, 0
	s_mov_b64 s[18:19], 0
	s_nop 3
	global_load_dword v2, v173, s[14:15] sc1
	s_waitcnt vmcnt(0)
	v_cmp_lt_u32_e32 vcc, v2, v204
	s_and_saveexec_b64 s[14:15], vcc
	s_cbranch_execz .LBB0_408
	s_mov_b32 s39, 1
	s_branch .LBB0_401

.LBB0_1447:
	s_or_b64 exec, exec, s[10:11]
	v_cvt_f32_u32_e32 v6, v4
	s_waitcnt vmcnt(0)
	v_readfirstlane_b32 s10, v5
	v_sub_u32_e32 v5, 0, v4
	v_rcp_iflag_f32_e32 v6, v6
	v_add_u32_e32 v7, s10, v3
	v_mul_f32_e32 v6, 0x4f7ffffe, v6
	v_cvt_u32_f32_e32 v6, v6
	v_mul_lo_u32 v3, v5, v6
	v_mul_hi_u32 v3, v6, v3
	v_add_u32_e32 v3, v6, v3
	v_mul_hi_u32 v3, v7, v3
	v_mul_lo_u32 v5, v3, v4
	v_sub_u32_e32 v5, v7, v5
	v_add_u32_e32 v6, 1, v3
	v_cmp_ge_u32_e32 vcc, v5, v4
	s_nop 1
	v_cndmask_b32_e32 v3, v3, v6, vcc
	v_sub_u32_e32 v6, v5, v4
	v_cndmask_b32_e32 v5, v5, v6, vcc
	v_add_u32_e32 v6, 1, v3
	v_cmp_ge_u32_e32 vcc, v5, v4
	v_add_u32_e32 v5, 1, v7
	s_nop 0
	v_cndmask_b32_e32 v3, v3, v6, vcc
	v_mul_lo_u32 v6, v4, v3
	v_add_u32_e32 v4, v6, v4
	v_cmp_ne_u32_e32 vcc, v5, v4
	s_and_saveexec_b64 s[10:11], vcc
	s_xor_b64 s[10:11], exec, s[10:11]
	s_cbranch_execz .LBB0_1461
	v_readlane_b32 s14, v245, 63
	v_readlane_b32 s15, v244, 0
	s_waitcnt lgkmcnt(0)
	v_add_u32_e32 v204, 1, v3
	v_mul_lo_u32 v204, v204, v2
	s_nop 3
	global_load_dword v2, v173, s[14:15] sc1
	s_waitcnt vmcnt(0)
	v_cmp_lt_u32_e32 vcc, v2, v204
	s_and_saveexec_b64 s[14:15], vcc
	s_cbranch_execz .LBB0_1460
	s_mov_b32 s38, 1
	s_mov_b64 s[18:19], 0
	s_branch .LBB0_1451

.LBB0_1453:
	v_readlane_b32 s22, v245, 63
	v_readlane_b32 s23, v244, 0
	s_add_i32 s38, s38, 1
	s_mov_b64 s[28:29], -1
	s_nop 2
	global_load_dword v2, v173, s[22:23] sc1
	s_waitcnt vmcnt(0)
	v_cmp_ge_u32_e32 vcc, v2, v204
	s_orn2_b64 s[22:23], vcc, exec
	s_branch .LBB0_1450

.LBB0_1464:
	s_or_b64 exec, exec, s[14:15]
	s_waitcnt vmcnt(0)
	v_readfirstlane_b32 s10, v4
	v_cvt_f32_u32_e32 v4, v2
	v_sub_u32_e32 v5, 0, v2
	v_add_u32_e32 v3, s10, v3
	v_readlane_b32 s10, v244, 1
	v_rcp_iflag_f32_e32 v4, v4
	v_readlane_b32 s11, v244, 2
	s_mov_b64 s[14:15], -1
	v_mul_f32_e32 v4, 0x4f7ffffe, v4
	v_cvt_u32_f32_e32 v4, v4
	v_mul_lo_u32 v5, v5, v4
	v_mul_hi_u32 v5, v4, v5
	v_add_u32_e32 v4, v4, v5
	v_mul_hi_u32 v4, v3, v4
	v_mul_lo_u32 v5, v4, v2
	v_sub_u32_e32 v5, v3, v5
	v_cmp_ge_u32_e32 vcc, v5, v2
	v_add_u32_e32 v6, 1, v4
	v_add_u32_e32 v3, 1, v3
	v_cndmask_b32_e32 v4, v4, v6, vcc
	v_sub_u32_e32 v6, v5, v2
	v_cndmask_b32_e32 v5, v5, v6, vcc
	v_cmp_ge_u32_e32 vcc, v5, v2
	v_add_u32_e32 v5, 1, v4
	s_nop 0
	v_cndmask_b32_e32 v4, v4, v5, vcc
	v_mul_lo_u32 v5, v2, v4
	v_add_u32_e32 v2, v5, v2
	v_mov_b32_e32 v204, v2
	v_cmp_ne_u32_e32 vcc, v3, v2
	v_mov_b64_e32 v[2:3], s[10:11]
	s_and_saveexec_b64 s[10:11], vcc
	s_cbranch_execz .LBB0_1476
	v_readlane_b32 s14, v245, 63
	v_readlane_b32 s15, v244, 0
	s_mov_b64 s[18:19], 0
	s_nop 3
	global_load_dword v2, v173, s[14:15] sc1
	s_waitcnt vmcnt(0)
	v_cmp_lt_u32_e32 vcc, v2, v204
	s_and_saveexec_b64 s[14:15], vcc
	s_cbranch_execz .LBB0_1475
	s_mov_b32 s38, 1
	s_branch .LBB0_1468
